# hot loop heads (GEMM K-loops, attention tile loop) aligned to 64 bytes
# speedup vs baseline: 1.0020x; 1.0020x over previous
; template <class Epi>
; DI void gemm_phase(LAS unsigned char* lds, const Gemm g, const StaticOrder& S_, const Epi& E) {
;     ...
;         const bool has_next = S_.next(ui + 1, nxt);
;         const char* nA0 = has_next ? (const char*)g.A0 + (size_t)nxt.pm * tstepA : cA0; const char* nB0 = has_next ? (const char*)g.B0 + (size_t)nxt.pn * tstepB : cB0;
;     ...
;         for (int a = 0; a < 2; ++a)
; #pragma unroll
;             for (int b = 0; b < 2; ++b)
; #pragma unroll
;                 for (int m = 0; m < 4; ++m)
; #pragma unroll
;                     for (int n = 0; n < 2; ++n) acc[a][b][m][n] = (f32x4){0.f, 0.f, 0.f, 0.f};
;         cur = nxt; ++ui;
;         cA0 = (const char*)g.A0 + (size_t)cur.pm * tstepA; cA1 = (const char*)g.A1 + (size_t)cur.pm * tstepA;
;         cB0 = (const char*)g.B0 + (size_t)cur.pn * tstepB; cB1 = (const char*)g.B1 + (size_t)cur.pn * tstepB;
.LBB0_113:
	s_add_u32 s18, s8, s14
	s_addc_u32 s51, s9, s15
	s_add_u32 s53, s65, s16
	s_addc_u32 s91, s66, s17
	s_ashr_i32 s43, s42, 31
	s_lshl_b64 s[14:15], s[42:43], 20
	v_cmp_lt_i64_e32 vcc, s[44:45], v[194:195]
	s_add_u32 s44, s8, s14
	s_addc_u32 s45, s9, s15
	s_and_b64 s[16:17], vcc, exec
	s_cselect_b32 s43, s45, s7
	s_cselect_b32 s92, s44, s6
	s_ashr_i32 s41, s40, 31
	s_lshl_b64 s[16:17], s[40:41], 20
	s_add_u32 s46, s65, s16
	s_addc_u32 s47, s66, s17
	s_and_b64 s[54:55], vcc, exec
	v_mov_b32_e32 v0, 0
	s_cselect_b32 s41, s47, s49
	s_cselect_b32 s93, s46, s48
	s_mov_b32 s56, -2
	s_mov_b64 s[54:55], 0x80080
	v_mov_b32_e32 v1, v0
	v_mov_b32_e32 v2, v0
	v_mov_b32_e32 v3, v0
	v_mov_b32_e32 v4, v0
	v_mov_b32_e32 v5, v0
	v_mov_b32_e32 v6, v0
	v_mov_b32_e32 v7, v0
	s_waitcnt vmcnt(0)
	v_mov_b32_e32 v16, v0
	v_mov_b32_e32 v17, v0
	v_mov_b32_e32 v18, v0
	v_mov_b32_e32 v19, v0
	v_mov_b32_e32 v20, v0
	v_mov_b32_e32 v21, v0
	v_mov_b32_e32 v22, v0
	v_mov_b32_e32 v23, v0
	v_mov_b32_e32 v32, v0
	v_mov_b32_e32 v33, v0
	v_mov_b32_e32 v34, v0
	v_mov_b32_e32 v35, v0
	v_mov_b32_e32 v36, v0
	v_mov_b32_e32 v37, v0
	v_mov_b32_e32 v38, v0
	v_mov_b32_e32 v39, v0
	v_mov_b32_e32 v48, v0
	v_mov_b32_e32 v49, v0
	v_mov_b32_e32 v50, v0
	v_mov_b32_e32 v51, v0
	v_mov_b32_e32 v52, v0
	v_mov_b32_e32 v53, v0
	v_mov_b32_e32 v54, v0
	v_mov_b32_e32 v55, v0
	v_mov_b32_e32 v8, v0
	v_mov_b32_e32 v9, v0
	v_mov_b32_e32 v10, v0
	v_mov_b32_e32 v11, v0
	v_mov_b32_e32 v12, v0
	v_mov_b32_e32 v13, v0
	v_mov_b32_e32 v14, v0
	v_mov_b32_e32 v15, v0
	v_mov_b32_e32 v24, v0
	v_mov_b32_e32 v25, v0
	v_mov_b32_e32 v26, v0
	v_mov_b32_e32 v27, v0
	v_mov_b32_e32 v28, v0
	v_mov_b32_e32 v29, v0
	v_mov_b32_e32 v30, v0
	v_mov_b32_e32 v31, v0
	v_mov_b32_e32 v40, v0
	v_mov_b32_e32 v41, v0
	v_mov_b32_e32 v42, v0
	v_mov_b32_e32 v43, v0
	v_mov_b32_e32 v44, v0
	v_mov_b32_e32 v45, v0
	v_mov_b32_e32 v46, v0
	v_mov_b32_e32 v47, v0
	v_mov_b32_e32 v56, v0
	v_mov_b32_e32 v57, v0
	v_mov_b32_e32 v58, v0
	v_mov_b32_e32 v59, v0
	v_mov_b32_e32 v60, v0
	v_mov_b32_e32 v61, v0
	v_mov_b32_e32 v62, v0
	v_mov_b32_e32 v63, v0
	v_mov_b32_e32 v64, v0
	v_mov_b32_e32 v65, v0
	v_mov_b32_e32 v66, v0
	v_mov_b32_e32 v67, v0
	v_mov_b32_e32 v68, v0
	v_mov_b32_e32 v69, v0
	v_mov_b32_e32 v70, v0
	v_mov_b32_e32 v71, v0
	v_mov_b32_e32 v80, v0
	v_mov_b32_e32 v81, v0
	v_mov_b32_e32 v82, v0
	v_mov_b32_e32 v83, v0
	v_mov_b32_e32 v84, v0
	v_mov_b32_e32 v85, v0
	v_mov_b32_e32 v86, v0
	v_mov_b32_e32 v87, v0
	v_mov_b32_e32 v96, v0
	v_mov_b32_e32 v97, v0
	v_mov_b32_e32 v98, v0
	v_mov_b32_e32 v99, v0
	v_mov_b32_e32 v100, v0
	v_mov_b32_e32 v101, v0
	v_mov_b32_e32 v102, v0
	v_mov_b32_e32 v103, v0
	v_mov_b32_e32 v112, v0
	v_mov_b32_e32 v113, v0
	v_mov_b32_e32 v114, v0
	v_mov_b32_e32 v115, v0
	v_mov_b32_e32 v116, v0
	v_mov_b32_e32 v117, v0
	v_mov_b32_e32 v118, v0
	v_mov_b32_e32 v119, v0
	v_mov_b32_e32 v72, v0
	v_mov_b32_e32 v73, v0
	v_mov_b32_e32 v74, v0
	v_mov_b32_e32 v75, v0
	v_mov_b32_e32 v76, v0
	v_mov_b32_e32 v77, v0
	v_mov_b32_e32 v78, v0
	v_mov_b32_e32 v79, v0
	v_mov_b32_e32 v88, v0
	v_mov_b32_e32 v89, v0
	v_mov_b32_e32 v90, v0
	v_mov_b32_e32 v91, v0
	v_mov_b32_e32 v92, v0
	v_mov_b32_e32 v93, v0
	v_mov_b32_e32 v94, v0
	v_mov_b32_e32 v95, v0
	v_mov_b32_e32 v104, v0
	v_mov_b32_e32 v105, v0
	v_mov_b32_e32 v106, v0
	v_mov_b32_e32 v107, v0
	v_mov_b32_e32 v108, v0
	v_mov_b32_e32 v109, v0
	v_mov_b32_e32 v110, v0
	v_mov_b32_e32 v111, v0
	v_mov_b32_e32 v120, v0
	v_mov_b32_e32 v121, v0
	v_mov_b32_e32 v122, v0
	v_mov_b32_e32 v123, v0
	v_mov_b32_e32 v124, v0
	v_mov_b32_e32 v125, v0
	v_mov_b32_e32 v126, v0
	v_mov_b32_e32 v127, v0
	v_lshl_add_u64 v[128:129], s[6:7], 0, v[190:191]
	v_lshl_add_u64 v[130:131], s[6:7], 0, v[192:193]
	.p2alignl 6, 3212836864

; #define SLOAD(i, k0) do { sr_[i].vs0 = *(const bf16x8*)(&Vh[(size_t)((k0) + sr) * LDK + sc]); sr_[i].vs1 = *(const bf16x8*)(&Vh[(size_t)((k0) + 32 + sr) * LDK + sc]); \
;     sr_[i].ks0 = *(const bf16x8*)(&Kh[(size_t)((k0) + sr) * LDK + sc]); sr_[i].ks1 = *(const bf16x8*)(&Kh[(size_t)((k0) + 32 + sr) * LDK + sc]); } while (0)
; #define SWRITE(b, i) do { *(bf16x8*)(V_lds + (b) * SHM_V + vst0) = sr_[i].vs0;          \
;     *(bf16x8*)(V_lds + (b) * SHM_V + vst1) = sr_[i].vs1; const int kc = sc * 2;               \
;     *(bf16x8*)(K_lds + (b) * SHM_K + KSWZ(sr, kc)) = sr_[i].ks0;                       \
;     *(bf16x8*)(K_lds + (b) * SHM_K + KSWZ(32 + sr, kc)) = sr_[i].ks1; } while (0)
; #define SWAIT() asm volatile("s_waitcnt vmcnt(4)" ::: "memory")
; DI void partialSM(f32x16& p0, f32x16& p1, float& m_reg, float& mn, float& alpha) {
;     constexpr float C = SCALE * 1.4426950408889634f;
;     float pmax = p0[0];
; #pragma unroll
;     for (int r = 1; r < 16; ++r) pmax = fmaxf(pmax, p0[r]);
; #pragma unroll
;     for (int r = 0; r < 16; ++r) pmax = fmaxf(pmax, p1[r]);
;     { auto rr = __builtin_amdgcn_permlane32_swap(__float_as_uint(pmax), __float_as_uint(pmax), false, false);
;       pmax = fmaxf(__uint_as_float(rr[0]), __uint_as_float(rr[1])); }
;     if (__builtin_expect(__all(pmax - m_reg <= THR / SCALE), 1)) { mn = m_reg; alpha = 1.f; }
;     else { mn = fmaxf(m_reg, pmax); alpha = __builtin_amdgcn_exp2f((m_reg - mn) * C); m_reg = mn; }
;     const float mnC = -mn * C;
; #pragma unroll
;     for (int r = 0; r < 16; ++r) p0[r] = fmaf(p0[r], C, mnC);
; #pragma unroll
;     for (int r = 0; r < 16; ++r) p1[r] = fmaf(p1[r], C, mnC);
; #pragma unroll
;     for (int r = 0; r < 16; ++r) p0[r] = __builtin_amdgcn_exp2f(p0[r]);
; }
; DI void attn_item(const bf16_t* __restrict__ Qw_, const bf16_t* __restrict__ Kh, const bf16_t* __restrict__ Vh, const bf16_t* Gw, bf16_t* Ow,
;                   int NT, int kt0, int qw, float sinkv, char* lds) {
;     ...
;     qkt(pA0, pA1, K_lds, qr, r32, hi); maskT(pA0, pA1, kt0, qw, r32, hi); partialSM(pA0, pA1, m_reg, mnA, alA);
;     SLOAD(SO, 64); if (2 < NT) SLOAD(SE, 128);
;     SWAIT(); SWRITE(1, SO); __syncthreads();
.LBB0_240:
	s_nop 8
	v_max_f32_e32 v34, v19, v19
	v_max_f32_e32 v35, v18, v18
	v_max_f32_e32 v34, v35, v34
	v_max3_f32 v34, v34, v20, v21
	v_max3_f32 v34, v34, v22, v23
	v_max3_f32 v51, v34, v24, v25
	global_load_dwordx4 v[34:37], v204, s[18:19]
	global_load_dwordx4 v[38:41], v205, s[18:19]
	global_load_dwordx4 v[42:45], v204, s[4:5]
	global_load_dwordx4 v[46:49], v205, s[4:5]
	global_load_dwordx4 v[134:137], v206, s[4:5]
	global_load_dwordx4 v[138:141], v206, s[18:19]
	global_load_dwordx4 v[142:145], v207, s[4:5]
	global_load_dwordx4 v[130:133], v207, s[18:19]
	v_max3_f32 v51, v51, v26, v27
	v_max3_f32 v51, v51, v28, v29
	v_max3_f32 v51, v51, v30, v31
	v_max3_f32 v51, v51, v32, v33
	v_max3_f32 v51, v51, v2, v3
	v_max3_f32 v51, v51, v4, v5
	v_max3_f32 v51, v51, v6, v7
	v_max3_f32 v51, v51, v8, v9
	v_max3_f32 v51, v51, v10, v11
	v_max3_f32 v51, v51, v12, v13
	s_lshr_b32 s56, s51, 1
	v_max3_f32 v51, v51, v14, v15
	s_ashr_i32 s15, s14, 31
	s_lshl_b32 s53, s17, 7
	s_ashr_i32 s17, s16, 31
	s_and_b32 s60, s56, 3
	v_max3_f32 v51, v51, v16, v17
	s_cmpk_eq_i32 s54, 0x7f
	v_mov_b32_e32 v52, v51
	s_cselect_b64 s[56:57], -1, 0
	s_nop 0
	v_permlane32_swap_b32_e32 v51, v52
	s_or_b64 s[20:21], s[20:21], s[56:57]
	v_max_f32_e32 v52, v52, v52
	v_max_f32_e32 v51, v51, v51
	s_and_b64 s[20:21], s[20:21], exec
	s_waitcnt vmcnt(8)
	v_mul_f32_e32 v50, 0x413504f3, v0
	v_max_f32_e32 v51, v51, v52
	s_cselect_b32 s56, 4, 6
	s_and_b32 s20, s52, 0x3fffffc0
	v_fmamk_f32 v52, v0, 0xc13504f3, v51
	v_max_f32_e32 v51, v50, v51
	s_lshl_b32 s20, s20, 2
	v_fma_f32 v0, v0, s43, -v51
	s_add_i32 s54, s20, 0
	v_mul_f32_e32 v0, 0x3e0293ee, v0
	s_add_i32 s54, s54, 0x10000
	v_cmp_ge_f32_e32 vcc, s44, v52
	v_exp_f32_e32 v0, v0
	s_cmp_eq_u64 vcc, exec
	s_cselect_b64 vcc, -1, 0
	v_cndmask_b32_e32 v162, v51, v50, vcc
	v_cndmask_b32_e64 v223, v0, 1.0, vcc
	v_mul_f32_e32 v0, 0xbe0293ee, v162
	v_mov_b32_e32 v50, v0
	v_pk_fma_f32 v[156:157], v[2:3], s[10:11], v[0:1] op_sel_hi:[1,0,0]
	v_lshl_add_u64 v[2:3], v[180:181], 0, s[16:17]
	v_fmamk_f32 v18, v18, 0x3e0293ee, v0
	v_fmamk_f32 v19, v19, 0x3e0293ee, v0
	v_fmamk_f32 v20, v20, 0x3e0293ee, v0
	v_fmamk_f32 v21, v21, 0x3e0293ee, v0
	v_fmamk_f32 v22, v22, 0x3e0293ee, v0
	v_fmamk_f32 v23, v23, 0x3e0293ee, v0
	v_fmamk_f32 v24, v24, 0x3e0293ee, v0
	v_fmamk_f32 v25, v25, 0x3e0293ee, v0
	v_fmamk_f32 v26, v26, 0x3e0293ee, v0
	v_fmamk_f32 v27, v27, 0x3e0293ee, v0
	v_fmamk_f32 v28, v28, 0x3e0293ee, v0
	v_fmamk_f32 v29, v29, 0x3e0293ee, v0
	v_fmamk_f32 v30, v30, 0x3e0293ee, v0
	v_fmamk_f32 v31, v31, 0x3e0293ee, v0
	v_fmamk_f32 v32, v32, 0x3e0293ee, v0
	v_fmac_f32_e32 v50, 0x3e0293ee, v33
	v_pk_fma_f32 v[154:155], v[4:5], s[10:11], v[0:1] op_sel_hi:[1,0,0]
	v_mad_u64_u32 v[4:5], s[4:5], v2, s35, 0
	v_pk_fma_f32 v[158:159], v[14:15], s[10:11], v[0:1] op_sel_hi:[1,0,0]
	v_exp_f32_e32 v177, v18
	v_exp_f32_e32 v228, v19
	v_exp_f32_e32 v175, v20
	v_exp_f32_e32 v227, v21
	v_exp_f32_e32 v174, v22
	v_exp_f32_e32 v176, v23
	v_exp_f32_e32 v172, v24
	v_exp_f32_e32 v173, v25
	v_exp_f32_e32 v169, v26
	v_exp_f32_e32 v171, v27
	v_exp_f32_e32 v168, v28
	v_exp_f32_e32 v170, v29
	v_exp_f32_e32 v165, v30
	v_exp_f32_e32 v167, v31
	v_exp_f32_e32 v164, v32
	v_exp_f32_e32 v166, v50
	v_mad_i32_i24 v3, v3, s35, v5
	v_lshl_or_b32 v2, s60, 8, v4
	v_mov_b32_e32 v14, v1
	v_mov_b32_e32 v15, v1
	v_pk_fma_f32 v[152:153], v[16:17], s[10:11], v[0:1] op_sel_hi:[1,0,0]
	v_pk_fma_f32 v[160:161], v[12:13], s[10:11], v[0:1] op_sel_hi:[1,0,0]
	v_pk_fma_f32 v[146:147], v[10:11], s[10:11], v[0:1] op_sel_hi:[1,0,0]
	v_pk_fma_f32 v[148:149], v[8:9], s[10:11], v[0:1] op_sel_hi:[1,0,0]
	v_pk_fma_f32 v[150:151], v[6:7], s[10:11], v[0:1] op_sel_hi:[1,0,0]
	s_waitcnt vmcnt(4)
	s_waitcnt vmcnt(7)
	ds_write_b128 v208, v[34:37] offset:16384
	s_waitcnt vmcnt(6)
	ds_write_b128 v209, v[38:41] offset:16384
	s_waitcnt vmcnt(5)
	ds_write_b128 v210, v[42:45] offset:49152
	s_waitcnt vmcnt(4)
	ds_write_b128 v211, v[46:49] offset:49152
	v_lshl_add_u64 v[186:187], v[182:183], 0, v[2:3]
	v_mov_b32_e32 v0, v1
	v_mov_b32_e32 v2, v1
	v_mov_b32_e32 v3, v1
	v_mov_b32_e32 v4, v1
	v_mov_b32_e32 v5, v1
	v_mov_b32_e32 v6, v1
	v_mov_b32_e32 v7, v1
	v_mov_b32_e32 v8, v1
	v_mov_b32_e32 v9, v1
	v_mov_b32_e32 v10, v1
	v_mov_b32_e32 v11, v1
	v_mov_b32_e32 v12, v1
	v_mov_b32_e32 v13, v1
	v_mov_b64_e32 v[64:65], v[14:15]
	v_mov_b64_e32 v[48:49], v[14:15]
	v_mov_b64_e32 v[32:33], v[14:15]
	v_mov_b64_e32 v[62:63], v[12:13]
	v_mov_b64_e32 v[60:61], v[10:11]
	v_mov_b64_e32 v[58:59], v[8:9]
	v_mov_b64_e32 v[56:57], v[6:7]
	v_mov_b64_e32 v[54:55], v[4:5]
	v_mov_b64_e32 v[52:53], v[2:3]
	v_mov_b64_e32 v[50:51], v[0:1]
	v_mov_b64_e32 v[46:47], v[12:13]
	v_mov_b64_e32 v[44:45], v[10:11]
	v_mov_b64_e32 v[42:43], v[8:9]
	v_mov_b64_e32 v[40:41], v[6:7]
	v_mov_b64_e32 v[38:39], v[4:5]
	v_mov_b64_e32 v[36:37], v[2:3]
	v_mov_b64_e32 v[34:35], v[0:1]
	v_mov_b64_e32 v[30:31], v[12:13]
	v_mov_b64_e32 v[28:29], v[10:11]
	v_mov_b64_e32 v[26:27], v[8:9]
	v_mov_b64_e32 v[24:25], v[6:7]
	v_mov_b64_e32 v[22:23], v[4:5]
	v_mov_b64_e32 v[20:21], v[2:3]
	v_mov_b64_e32 v[18:19], v[0:1]
	v_mov_b64_e32 v[16:17], v[14:15]
	s_mov_b32 s57, 2
	v_mov_b32_e32 v221, 1.0
	v_lshl_add_u32 v222, v188, 2, s54
	s_sub_i32 s58, 0, s58
	s_add_i32 s59, s40, s16
	v_add_u32_e32 v224, s16, v199
	v_mov_b64_e32 v[14:15], v[12:13]
	v_mov_b64_e32 v[12:13], v[10:11]
	v_mov_b64_e32 v[10:11], v[8:9]
	v_mov_b64_e32 v[8:9], v[6:7]
	v_mov_b64_e32 v[6:7], v[4:5]
	v_mov_b64_e32 v[4:5], v[2:3]
	v_mov_b64_e32 v[2:3], v[0:1]
	s_waitcnt lgkmcnt(0)
	s_barrier
	.p2alignl 6, 3212836864

; template <class Epi>
; DI void gemm_phase(LAS unsigned char* lds, const Gemm g, const StaticOrder& S_, const Epi& E) {
;     ...
;         for (int hf = 0; hf < (Epi::MID ? 2 : 1); ++hf) {
;         const int tb = Epi::MID ? hf * ksplit : 0, te = Epi::MID ? (hf + 1) * ksplit : nt;
;         for (int t = tb; t < te; t += 2) {
;             const bool last = (t == nt - 2);
;             const bool hA = (t >= ksplit), hB = (t + 2 >= ksplit);
;             const char* a1 = (hA ? cA1 : cA0) + (size_t)(t + 1) * kstep;
.LBB0_449:
	s_xor_b64 s[42:43], s[44:45], -1
	s_add_i32 s81, s14, 32
	s_lshl_b64 s[46:47], s[14:15], 7
	.p2alignl 6, 3212836864

; template <class Epi>
; DI void gemm_phase(LAS unsigned char* lds, const Gemm g, const StaticOrder& S_, const Epi& E) {
;     ...
;         const bool has_next = S_.next(ui + 1, nxt);
;         const char* nA0 = has_next ? (const char*)g.A0 + (size_t)nxt.pm * tstepA : cA0; const char* nB0 = has_next ? (const char*)g.B0 + (size_t)nxt.pn * tstepB : cB0;
;     ...
;         for (int a = 0; a < 2; ++a)
; #pragma unroll
;             for (int b = 0; b < 2; ++b)
; #pragma unroll
;                 for (int m = 0; m < 4; ++m)
; #pragma unroll
;                     for (int n = 0; n < 2; ++n) acc[a][b][m][n] = (f32x4){0.f, 0.f, 0.f, 0.f};
;         cur = nxt; ++ui;
;         cA0 = (const char*)g.A0 + (size_t)cur.pm * tstepA; cA1 = (const char*)g.A1 + (size_t)cur.pm * tstepA;
;         cB0 = (const char*)g.B0 + (size_t)cur.pn * tstepB; cB1 = (const char*)g.B1 + (size_t)cur.pn * tstepB;
.LBB0_524:
	s_add_u32 s37, s10, s12
	s_addc_u32 s39, s11, s13
	s_add_u32 s68, s51, s14
	s_addc_u32 s69, s52, s15
	s_ashr_i32 s23, s22, 31
	s_lshl_b64 s[12:13], s[22:23], 20
	v_cmp_lt_i64_e32 vcc, s[30:31], v[142:143]
	s_add_u32 s30, s10, s12
	s_addc_u32 s31, s11, s13
	s_and_b64 s[14:15], vcc, exec
	s_cselect_b32 s23, s31, s41
	s_cselect_b32 s70, s30, s40
	s_ashr_i32 s21, s20, 31
	s_lshl_b64 s[14:15], s[20:21], 20
	s_add_u32 s34, s51, s14
	s_addc_u32 s35, s52, s15
	s_and_b64 s[44:45], vcc, exec
	v_mov_b32_e32 v0, 0
	s_cselect_b32 s21, s35, s43
	s_cselect_b32 s71, s34, s42
	v_lshl_add_u64 v[146:147], s[40:41], 0, v[138:139]
	v_lshl_add_u64 v[148:149], s[40:41], 0, v[140:141]
	s_mov_b32 s46, -2
	s_mov_b64 s[44:45], 0x80080
	v_mov_b32_e32 v1, v0
	v_mov_b32_e32 v2, v0
	v_mov_b32_e32 v3, v0
	v_mov_b32_e32 v4, v0
	s_waitcnt lgkmcnt(0)
	v_mov_b32_e32 v5, v0
	v_mov_b32_e32 v6, v0
	v_mov_b32_e32 v7, v0
	v_mov_b32_e32 v16, v0
	v_mov_b32_e32 v17, v0
	v_mov_b32_e32 v18, v0
	v_mov_b32_e32 v19, v0
	v_mov_b32_e32 v20, v0
	v_mov_b32_e32 v21, v0
	v_mov_b32_e32 v22, v0
	v_mov_b32_e32 v23, v0
	v_mov_b32_e32 v32, v0
	v_mov_b32_e32 v33, v0
	v_mov_b32_e32 v34, v0
	v_mov_b32_e32 v35, v0
	v_mov_b32_e32 v36, v0
	v_mov_b32_e32 v37, v0
	v_mov_b32_e32 v38, v0
	v_mov_b32_e32 v39, v0
	v_mov_b32_e32 v48, v0
	v_mov_b32_e32 v49, v0
	v_mov_b32_e32 v50, v0
	v_mov_b32_e32 v51, v0
	v_mov_b32_e32 v52, v0
	v_mov_b32_e32 v53, v0
	v_mov_b32_e32 v54, v0
	v_mov_b32_e32 v55, v0
	v_mov_b32_e32 v8, v0
	v_mov_b32_e32 v9, v0
	v_mov_b32_e32 v10, v0
	v_mov_b32_e32 v11, v0
	v_mov_b32_e32 v12, v0
	v_mov_b32_e32 v13, v0
	v_mov_b32_e32 v14, v0
	v_mov_b32_e32 v15, v0
	v_mov_b32_e32 v24, v0
	v_mov_b32_e32 v25, v0
	v_mov_b32_e32 v26, v0
	v_mov_b32_e32 v27, v0
	v_mov_b32_e32 v28, v0
	v_mov_b32_e32 v29, v0
	v_mov_b32_e32 v30, v0
	v_mov_b32_e32 v31, v0
	v_mov_b32_e32 v40, v0
	v_mov_b32_e32 v41, v0
	v_mov_b32_e32 v42, v0
	v_mov_b32_e32 v43, v0
	v_mov_b32_e32 v44, v0
	v_mov_b32_e32 v45, v0
	v_mov_b32_e32 v46, v0
	v_mov_b32_e32 v47, v0
	v_mov_b32_e32 v56, v0
	v_mov_b32_e32 v57, v0
	v_mov_b32_e32 v58, v0
	v_mov_b32_e32 v59, v0
	v_mov_b32_e32 v60, v0
	v_mov_b32_e32 v61, v0
	v_mov_b32_e32 v62, v0
	v_mov_b32_e32 v63, v0
	v_mov_b32_e32 v64, v0
	v_mov_b32_e32 v65, v0
	v_mov_b32_e32 v66, v0
	v_mov_b32_e32 v67, v0
	v_mov_b32_e32 v68, v0
	v_mov_b32_e32 v69, v0
	v_mov_b32_e32 v70, v0
	v_mov_b32_e32 v71, v0
	v_mov_b32_e32 v80, v0
	v_mov_b32_e32 v81, v0
	v_mov_b32_e32 v82, v0
	v_mov_b32_e32 v83, v0
	v_mov_b32_e32 v84, v0
	v_mov_b32_e32 v85, v0
	v_mov_b32_e32 v86, v0
	v_mov_b32_e32 v87, v0
	v_mov_b32_e32 v96, v0
	v_mov_b32_e32 v97, v0
	v_mov_b32_e32 v98, v0
	v_mov_b32_e32 v99, v0
	v_mov_b32_e32 v100, v0
	v_mov_b32_e32 v101, v0
	v_mov_b32_e32 v102, v0
	v_mov_b32_e32 v103, v0
	v_mov_b32_e32 v112, v0
	v_mov_b32_e32 v113, v0
	v_mov_b32_e32 v114, v0
	v_mov_b32_e32 v115, v0
	v_mov_b32_e32 v116, v0
	v_mov_b32_e32 v117, v0
	v_mov_b32_e32 v118, v0
	v_mov_b32_e32 v119, v0
	v_mov_b32_e32 v72, v0
	v_mov_b32_e32 v73, v0
	v_mov_b32_e32 v74, v0
	v_mov_b32_e32 v75, v0
	v_mov_b32_e32 v76, v0
	v_mov_b32_e32 v77, v0
	v_mov_b32_e32 v78, v0
	v_mov_b32_e32 v79, v0
	v_mov_b32_e32 v88, v0
	v_mov_b32_e32 v89, v0
	v_mov_b32_e32 v90, v0
	v_mov_b32_e32 v91, v0
	v_mov_b32_e32 v92, v0
	v_mov_b32_e32 v93, v0
	v_mov_b32_e32 v94, v0
	v_mov_b32_e32 v95, v0
	v_mov_b32_e32 v104, v0
	v_mov_b32_e32 v105, v0
	v_mov_b32_e32 v106, v0
	v_mov_b32_e32 v107, v0
	v_mov_b32_e32 v108, v0
	v_mov_b32_e32 v109, v0
	v_mov_b32_e32 v110, v0
	v_mov_b32_e32 v111, v0
	v_mov_b32_e32 v120, v0
	v_mov_b32_e32 v121, v0
	v_mov_b32_e32 v122, v0
	v_mov_b32_e32 v123, v0
	v_mov_b32_e32 v124, v0
	v_mov_b32_e32 v125, v0
	v_mov_b32_e32 v126, v0
	v_mov_b32_e32 v127, v0
	.p2alignl 6, 3212836864
